# GEMM phases: static s_setprio 1 for waves 0-3 during each GEMM phase (template per-block flips already removed)
# speedup vs baseline: 1.0093x; 1.0045x over previous
.LBB0_234:
	s_or_b64 exec, exec, s[0:1]
	v_readlane_b32 s0, v241, 3
	s_waitcnt vmcnt(2)
	v_mov_b32_e32 v6, v204
	v_readlane_b32 s1, v241, 4
	s_waitcnt lgkmcnt(0)
	s_barrier
	v_readfirstlane_b32 s100, v204
	s_cmp_lt_u32 s100, 0x100
	s_cbranch_scc0 .Lprio_skip_8
	s_setprio 1
.Lprio_skip_8:
	s_and_b64 vcc, exec, s[0:1]
	v_readfirstlane_b32 s4, v6
	s_cbranch_vccz .LBB0_262
	v_lshlrev_b32_e32 v3, 4, v6
	v_add_u32_e32 v1, 0x2000, v3
	v_ashrrev_i32_e32 v0, 31, v1
	v_lshrrev_b32_e32 v0, 22, v0
	v_add_u32_e32 v0, v1, v0
	v_ashrrev_i32_e32 v0, 10, v0
	v_mul_i32_i24_e32 v2, 0x400, v0
	v_sub_u32_e32 v1, v1, v2
	v_lshrrev_b32_e32 v2, 4, v1
	v_bitop3_b32 v2, v2, v1, 32 bitop3:0x6c
	v_ashrrev_i32_e32 v1, 31, v2
	v_lshrrev_b32_e32 v1, 26, v1
	v_add_u32_e32 v4, v2, v1
	v_lshlrev_b32_e32 v5, 3, v0
	v_ashrrev_i32_e32 v1, 6, v4
	v_and_b32_e32 v5, -16, v5
	v_add_u32_e32 v5, v1, v5
	v_and_b32_e32 v7, 3, v1
	s_mov_b32 s0, 0x1fffe0
	s_waitcnt vmcnt(1)
	v_lshrrev_b32_e32 v8, 2, v5
	v_lshlrev_b32_e32 v9, 1, v5
	v_and_b32_e32 v4, 0xc0, v4
	v_and_or_b32 v7, v5, s0, v7
	v_and_b32_e32 v8, 4, v8
	v_and_b32_e32 v9, 24, v9
	v_sub_u32_e32 v2, v2, v4
	v_or3_b32 v7, v7, v8, v9
	v_lshlrev_b32_e32 v8, 5, v0
	v_ashrrev_i16_sdwa v2, v207, sext(v2) dst_sel:DWORD dst_unused:UNUSED_PAD src0_sel:DWORD src1_sel:BYTE_0
	v_and_b32_e32 v8, 32, v8
	v_bfe_i32 v2, v2, 0, 16
	v_add_lshl_u32 v4, v8, v2, 1
	v_lshl_add_u32 v128, v7, 11, v4
	v_lshl_add_u32 v130, v5, 11, v4
	v_bfe_i32 v4, v6, 27, 1
	v_lshrrev_b32_e32 v4, 22, v4
	v_add_u32_e32 v4, v3, v4
	v_and_b32_e32 v4, 0xfffffc00, v4
	v_sub_u32_e32 v3, v3, v4
	v_lshrrev_b32_e32 v4, 4, v3
	v_bitop3_b32 v5, v4, v3, 32 bitop3:0x6c
	v_ashrrev_i32_e32 v4, 31, v6
	v_lshrrev_b32_e32 v4, 26, v4
	v_ashrrev_i32_e32 v3, 31, v3
	v_add_u32_e32 v4, v6, v4
	v_lshrrev_b32_e32 v3, 26, v3
	v_ashrrev_i32_e32 v4, 6, v4
	v_add_u32_e32 v3, v5, v3
	v_lshlrev_b32_e32 v7, 3, v4
	v_ashrrev_i32_e32 v3, 6, v3
	v_and_b32_e32 v7, -16, v7
	v_add_u32_e32 v7, v3, v7
	v_and_b32_e32 v8, 3, v3
	v_lshrrev_b32_e32 v9, 2, v7
	v_lshlrev_b32_e32 v10, 1, v7
	v_and_or_b32 v8, v7, s0, v8
	v_and_b32_e32 v9, 4, v9
	v_and_b32_e32 v10, 24, v10
	v_or3_b32 v8, v8, v9, v10
	v_mul_i32_i24_e32 v10, 64, v3
	v_sub_u32_e32 v5, v5, v10
	s_ashr_i32 s5, s4, 6
	v_lshlrev_b32_e32 v9, 5, v4
	v_ashrrev_i16_sdwa v5, v207, sext(v5) dst_sel:DWORD dst_unused:UNUSED_PAD src0_sel:DWORD src1_sel:BYTE_0
	s_lshl_b32 s11, s5, 10
	v_and_b32_e32 v9, 32, v9
	v_bfe_i32 v5, v5, 0, 16
	v_add_lshl_u32 v9, v9, v5, 1
	s_add_i32 s13, s11, 0
	v_readlane_b32 s0, v241, 61
	v_lshl_add_u32 v172, v8, 11, v9
	s_add_i32 m0, s13, 0x10000
	v_readlane_b32 s1, v241, 62
	v_lshl_add_u32 v132, v7, 11, v9
	s_add_i32 s26, s13, 0x2000
	s_add_i32 s31, s13, 0x4000
	s_add_i32 s35, s13, 0x6000
	s_ashr_i32 s8, s4, 8
	global_load_lds_dwordx4 v172, s[0:1]
	s_add_i32 m0, s13, 0x12000
	s_nop 0
	global_load_lds_dwordx4 v128, s[0:1]
	v_readlane_b32 s0, v241, 55
	s_add_i32 m0, s13, 0x14000
	v_readlane_b32 s1, v241, 56
	s_nop 4
	global_load_lds_dwordx4 v172, s[0:1]
	s_add_i32 m0, s13, 0x16000
	s_cmp_eq_u32 s8, 1
	global_load_lds_dwordx4 v128, s[0:1]
	v_readlane_b32 s0, v241, 57
	s_mov_b32 m0, s13
	v_readlane_b32 s1, v241, 58
	s_nop 4
	global_load_lds_dwordx4 v132, s[0:1]
	s_mov_b32 m0, s26
	s_nop 0
	global_load_lds_dwordx4 v130, s[0:1]
	v_readlane_b32 s0, v241, 59
	s_mov_b32 m0, s31
	v_readlane_b32 s1, v241, 60
	s_nop 4
	global_load_lds_dwordx4 v132, s[0:1]
	s_mov_b32 m0, s35
	s_nop 0
	global_load_lds_dwordx4 v130, s[0:1]
	s_cselect_b64 s[0:1], -1, 0
	s_cmp_lg_u32 s8, 1
	s_cbranch_scc1 .LBB0_237
	s_barrier

.LBB0_262:
	s_setprio 0
	s_waitcnt vmcnt(0)
	s_waitcnt vmcnt(0)
	s_barrier
	s_mov_b64 s[0:1], exec
	v_readlane_b32 s4, v242, 0
	v_readlane_b32 s5, v242, 1
	s_and_b64 s[4:5], s[0:1], s[4:5]
	s_xor_b64 s[0:1], s[4:5], s[0:1]
	s_mov_b64 exec, s[4:5]
	s_cbranch_execz .LBB0_315
	v_readlane_b32 s4, v240, 27
	s_waitcnt vmcnt(0) expcnt(0) lgkmcnt(0)
	s_nop 0
	v_mov_b32_e32 v0, s4
	ds_read_b32 v2, v0
	v_readlane_b32 s4, v240, 28
	s_waitcnt lgkmcnt(0)
	v_cmp_ne_u32_e32 vcc, 0, v2
	v_mov_b32_e32 v0, s4
	ds_read_b32 v0, v0
	s_cbranch_vccnz .LBB0_278
	s_mov_b32 s11, 1
	s_branch .LBB0_266

.LBB0_904:
	s_or_b64 exec, exec, s[0:1]
	v_readlane_b32 s0, v242, 56
	s_add_u32 s11, s0, s52
	v_readlane_b32 s0, v242, 57
	s_addc_u32 s13, s0, s53
	v_readlane_b32 s4, v240, 48
	s_add_u32 s26, s11, 0x2000
	v_readlane_b32 s5, v240, 49
	s_addc_u32 s35, s13, 0
	s_mov_b64 s[0:1], -1
	s_and_b64 vcc, exec, s[4:5]
	s_waitcnt lgkmcnt(0)
	s_barrier
	v_readfirstlane_b32 s100, v204
	s_cmp_lt_u32 s100, 0x100
	s_cbranch_scc0 .Lprio_skip_6
	s_setprio 1
.Lprio_skip_6:
	s_cbranch_vccz .LBB0_924
	v_mov_b32_e32 v6, v204
	s_and_b64 vcc, exec, s[40:41]
	v_readfirstlane_b32 s4, v6
	s_cbranch_vccnz .LBB0_923
	v_lshlrev_b32_e32 v3, 4, v6
	v_add_u32_e32 v1, 0x2000, v3
	v_ashrrev_i32_e32 v0, 31, v1
	v_lshrrev_b32_e32 v0, 22, v0
	v_add_u32_e32 v0, v1, v0
	v_ashrrev_i32_e32 v0, 10, v0
	v_mul_i32_i24_e32 v2, 0x400, v0
	v_sub_u32_e32 v1, v1, v2
	v_lshrrev_b32_e32 v2, 4, v1
	v_bitop3_b32 v2, v2, v1, 32 bitop3:0x6c
	v_ashrrev_i32_e32 v1, 31, v2
	v_lshrrev_b32_e32 v1, 26, v1
	v_add_u32_e32 v4, v2, v1
	v_lshlrev_b32_e32 v5, 3, v0
	v_ashrrev_i32_e32 v1, 6, v4
	v_and_b32_e32 v5, -16, v5
	v_add_u32_e32 v5, v1, v5
	v_and_b32_e32 v7, 3, v1
	s_mov_b32 s0, 0x1fffe0
	v_lshrrev_b32_e32 v8, 2, v5
	v_lshlrev_b32_e32 v9, 1, v5
	v_and_b32_e32 v4, 0xc0, v4
	v_and_or_b32 v7, v5, s0, v7
	v_and_b32_e32 v8, 4, v8
	v_and_b32_e32 v9, 24, v9
	v_sub_u32_e32 v2, v2, v4
	v_or3_b32 v7, v7, v8, v9
	v_lshlrev_b32_e32 v8, 5, v0
	v_ashrrev_i16_sdwa v2, v207, sext(v2) dst_sel:DWORD dst_unused:UNUSED_PAD src0_sel:DWORD src1_sel:BYTE_0
	v_and_b32_e32 v8, 32, v8
	v_bfe_i32 v2, v2, 0, 16
	v_add_lshl_u32 v4, v8, v2, 1
	v_lshl_add_u32 v182, v7, 11, v4
	v_lshl_add_u32 v184, v5, 11, v4
	v_bfe_i32 v4, v6, 27, 1
	v_lshrrev_b32_e32 v4, 22, v4
	v_add_u32_e32 v4, v3, v4
	v_and_b32_e32 v4, 0xfffffc00, v4
	v_sub_u32_e32 v3, v3, v4
	v_lshrrev_b32_e32 v4, 4, v3
	v_bitop3_b32 v5, v4, v3, 32 bitop3:0x6c
	v_ashrrev_i32_e32 v4, 31, v6
	v_lshrrev_b32_e32 v4, 26, v4
	v_ashrrev_i32_e32 v3, 31, v3
	v_add_u32_e32 v4, v6, v4
	v_lshrrev_b32_e32 v3, 26, v3
	v_ashrrev_i32_e32 v4, 6, v4
	v_add_u32_e32 v3, v5, v3
	v_lshlrev_b32_e32 v7, 3, v4
	v_ashrrev_i32_e32 v3, 6, v3
	v_and_b32_e32 v7, -16, v7
	v_add_u32_e32 v7, v3, v7
	v_and_b32_e32 v8, 3, v3
	v_lshrrev_b32_e32 v9, 2, v7
	v_lshlrev_b32_e32 v10, 1, v7
	v_and_or_b32 v8, v7, s0, v8
	v_and_b32_e32 v9, 4, v9
	v_and_b32_e32 v10, 24, v10
	v_or3_b32 v8, v8, v9, v10
	v_mul_i32_i24_e32 v10, 64, v3
	v_sub_u32_e32 v5, v5, v10
	s_ashr_i32 s5, s4, 6
	v_lshlrev_b32_e32 v9, 5, v4
	v_ashrrev_i16_sdwa v5, v207, sext(v5) dst_sel:DWORD dst_unused:UNUSED_PAD src0_sel:DWORD src1_sel:BYTE_0
	s_lshl_b32 s31, s5, 10
	v_and_b32_e32 v9, 32, v9
	v_bfe_i32 v5, v5, 0, 16
	v_add_lshl_u32 v9, v9, v5, 1
	s_add_i32 s51, s31, 0
	v_readlane_b32 s0, v241, 45
	v_lshl_add_u32 v172, v8, 11, v9
	s_add_i32 m0, s51, 0x10000
	v_readlane_b32 s1, v241, 46
	v_lshl_add_u32 v186, v7, 11, v9
	s_add_i32 s60, s51, 0x2000
	s_add_i32 s61, s51, 0x4000
	s_add_i32 s62, s51, 0x6000
	s_ashr_i32 s8, s4, 8
	global_load_lds_dwordx4 v172, s[0:1]
	s_add_i32 m0, s51, 0x12000
	s_nop 0
	global_load_lds_dwordx4 v182, s[0:1]
	v_readlane_b32 s0, v241, 39
	s_add_i32 m0, s51, 0x14000
	v_readlane_b32 s1, v241, 40
	s_nop 4
	global_load_lds_dwordx4 v172, s[0:1]
	s_add_i32 m0, s51, 0x16000
	s_cmp_eq_u32 s8, 1
	global_load_lds_dwordx4 v182, s[0:1]
	v_readlane_b32 s0, v241, 41
	s_mov_b32 m0, s51
	v_readlane_b32 s1, v241, 42
	s_nop 4
	global_load_lds_dwordx4 v186, s[0:1]
	s_mov_b32 m0, s60
	s_nop 0
	global_load_lds_dwordx4 v184, s[0:1]
	v_readlane_b32 s0, v241, 43
	s_mov_b32 m0, s61
	v_readlane_b32 s1, v241, 44
	s_nop 4
	global_load_lds_dwordx4 v186, s[0:1]
	s_mov_b32 m0, s62
	s_nop 0
	global_load_lds_dwordx4 v184, s[0:1]
	s_cselect_b64 s[0:1], -1, 0
	s_cmp_lg_u32 s8, 1
	s_cbranch_scc1 .LBB0_908
	s_barrier

.LBB0_1032:
	s_setprio 0
	s_waitcnt vmcnt(0)
	s_barrier
	s_mov_b64 s[0:1], exec
	v_readlane_b32 s4, v242, 0
	v_readlane_b32 s5, v242, 1
	s_and_b64 s[4:5], s[0:1], s[4:5]
	s_mov_b64 exec, s[4:5]
	s_cbranch_execz .LBB0_1084
	v_readlane_b32 s4, v240, 27
	s_waitcnt vmcnt(0) expcnt(0) lgkmcnt(0)
	s_nop 0
	v_mov_b32_e32 v0, s4
	ds_read_b32 v2, v0
	v_readlane_b32 s4, v240, 28
	s_waitcnt lgkmcnt(0)
	v_cmp_ne_u32_e32 vcc, 0, v2
	v_mov_b32_e32 v0, s4
	ds_read_b32 v0, v0
	s_cbranch_vccnz .LBB0_1048
	s_mov_b32 s26, 1
	s_branch .LBB0_1036

.LBB0_1142:
	s_or_b64 exec, exec, s[0:1]
	v_readlane_b32 s0, v240, 44
	v_readlane_b32 s1, v240, 45
	s_mov_b32 s1, s27
	v_writelane_b32 v240, s0, 44
	s_add_u32 s11, s11, 0x5000
	s_addc_u32 s13, s13, 0
	v_writelane_b32 v240, s1, 45
	s_mul_i32 s26, s50, 0x6300
	v_readlane_b32 s0, v240, 42
	v_readlane_b32 s1, v240, 43
	s_mov_b32 s1, s27
	v_writelane_b32 v240, s0, 42
	s_lshl_b64 s[8:9], s[26:27], 2
	s_mul_i32 s4, s50, 0xb00
	v_writelane_b32 v240, s1, 43
	s_lshl_b32 s0, s50, 20
	s_mov_b32 s1, s27
	v_writelane_b32 v240, s0, 52
	s_mov_b32 s5, s27
	s_lshl_b64 s[4:5], s[4:5], 2
	v_writelane_b32 v240, s1, 53
	v_readlane_b32 s50, v242, 54
	v_readlane_b32 s0, v240, 40
	v_readlane_b32 s1, v240, 41
	s_mov_b32 s1, s27
	v_writelane_b32 v240, s0, 40
	s_mov_b64 s[38:39], 0
	v_readlane_b32 s51, v242, 55
	v_writelane_b32 v240, s1, 41
	v_writelane_b32 v240, s8, 54
	s_mov_b64 s[0:1], -1
	s_waitcnt lgkmcnt(0)
	v_writelane_b32 v240, s9, 55
	v_writelane_b32 v240, s4, 56
	s_barrier
	v_readfirstlane_b32 s100, v204
	s_cmp_lt_u32 s100, 0x100
	s_cbranch_scc0 .Lprio_skip_4
	s_setprio 1
.Lprio_skip_4:
	s_nop 0
	v_writelane_b32 v240, s5, 57
	s_branch .LBB0_1145

.LBB0_1144:
	s_or_b64 exec, exec, s[0:1]
	s_mov_b64 s[38:39], -1
	s_mov_b64 s[0:1], 0
	s_and_b64 vcc, exec, s[96:97]
	s_waitcnt lgkmcnt(0)
	s_barrier
	v_readfirstlane_b32 s100, v204
	s_cmp_lt_u32 s100, 0x100
	s_cbranch_scc0 .Lprio_skip_3
	s_setprio 1
.Lprio_skip_3:
	s_cbranch_vccz .LBB0_1145
	s_getpc_b64 s[98:99]

.LBB0_1161:
	s_setprio 0
	s_waitcnt vmcnt(0)
	s_waitcnt vmcnt(0)
	s_barrier
	s_mov_b64 s[4:5], exec
	v_readlane_b32 s8, v242, 0
	v_readlane_b32 s9, v242, 1
	s_and_b64 s[8:9], s[4:5], s[8:9]
	s_xor_b64 s[28:29], s[8:9], s[4:5]
	s_mov_b64 exec, s[8:9]
	s_cbranch_execz .LBB0_1214
	v_readlane_b32 s4, v240, 27
	s_waitcnt vmcnt(0) expcnt(0) lgkmcnt(0)
	s_nop 0
	v_mov_b32_e32 v0, s4
	ds_read_b32 v2, v0
	v_readlane_b32 s4, v240, 28
	s_waitcnt lgkmcnt(0)
	v_cmp_ne_u32_e32 vcc, 0, v2
	v_mov_b32_e32 v0, s4
	ds_read_b32 v0, v0
	s_cbranch_vccnz .LBB0_1177
	s_mov_b32 s26, 1
	s_branch .LBB0_1165

.LBB0_1399:
	s_or_b64 exec, exec, s[28:29]
	v_readlane_b32 s8, v241, 9
	v_mov_b32_e32 v18, v204
	v_readlane_b32 s9, v241, 10
	s_waitcnt lgkmcnt(0)
	s_barrier
	v_readfirstlane_b32 s100, v204
	s_cmp_lt_u32 s100, 0x100
	s_cbranch_scc0 .Lprio_skip_1
	s_setprio 1
.Lprio_skip_1:
	s_and_b64 vcc, exec, s[8:9]
	v_readfirstlane_b32 s4, v18
	s_cbranch_vccz .LBB0_1421
	v_lshlrev_b32_e32 v0, 4, v18
	v_add_u32_e32 v1, 0x2000, v0
	v_ashrrev_i32_e32 v2, 31, v1
	v_lshrrev_b32_e32 v2, 22, v2
	v_add_u32_e32 v2, v1, v2
	v_ashrrev_i32_e32 v2, 10, v2
	v_mul_i32_i24_e32 v3, 0x400, v2
	v_sub_u32_e32 v1, v1, v3
	v_lshrrev_b32_e32 v3, 4, v1
	v_bitop3_b32 v1, v3, v1, 32 bitop3:0x6c
	v_ashrrev_i32_e32 v3, 31, v1
	v_lshrrev_b32_e32 v3, 26, v3
	s_and_b64 s[0:1], s[0:1], exec
	v_add_u32_e32 v3, v1, v3
	v_lshlrev_b32_e32 v5, 3, v2
	s_mov_b32 s0, 0x1c32000
	v_ashrrev_i32_e32 v4, 6, v3
	v_and_b32_e32 v5, -16, v5
	v_lshlrev_b32_e32 v2, 5, v2
	s_cselect_b32 s0, s0, 0x1f32000
	v_add_u32_e32 v5, v4, v5
	v_and_b32_e32 v12, 32, v2
	v_and_b32_e32 v2, 0xc0, v3
	s_add_u32 s8, s82, s0
	v_and_b32_e32 v4, 3, v4
	s_mov_b32 s0, 0x7fffffe0
	v_lshrrev_b32_e32 v6, 2, v5
	v_lshlrev_b32_e32 v7, 1, v5
	v_sub_u32_e32 v1, v1, v2
	v_and_or_b32 v4, v5, s0, v4
	v_and_b32_e32 v6, 4, v6
	v_and_b32_e32 v7, 24, v7
	v_ashrrev_i16_sdwa v1, v207, sext(v1) dst_sel:DWORD dst_unused:UNUSED_PAD src0_sel:DWORD src1_sel:BYTE_0
	v_or3_b32 v4, v4, v6, v7
	v_bfe_i32 v13, v1, 0, 16
	v_mul_lo_u32 v4, v4, s35
	v_add_u32_e32 v1, v12, v13
	v_mul_lo_u32 v14, v5, s35
	v_add_lshl_u32 v182, v4, v1, 1
	v_add_lshl_u32 v184, v1, v14, 1
	v_bfe_i32 v1, v18, 27, 1
	v_lshrrev_b32_e32 v1, 22, v1
	v_add_u32_e32 v1, v0, v1
	v_and_b32_e32 v1, 0xfffffc00, v1
	v_sub_u32_e32 v0, v0, v1
	v_ashrrev_i32_e32 v2, 31, v18
	v_lshrrev_b32_e32 v1, 4, v0
	v_lshrrev_b32_e32 v2, 26, v2
	v_bitop3_b32 v1, v1, v0, 32 bitop3:0x6c
	v_ashrrev_i32_e32 v0, 31, v0
	v_add_u32_e32 v2, v18, v2
	v_lshrrev_b32_e32 v0, 26, v0
	v_ashrrev_i32_e32 v2, 6, v2
	v_add_u32_e32 v0, v1, v0
	v_lshlrev_b32_e32 v3, 3, v2
	v_ashrrev_i32_e32 v0, 6, v0
	v_and_b32_e32 v3, -16, v3
	v_add_u32_e32 v3, v0, v3
	v_and_b32_e32 v4, 3, v0
	v_and_or_b32 v4, v3, s0, v4
	v_readlane_b32 s0, v241, 33
	s_addc_u32 s9, s83, 0
	s_lshl_b32 s31, s35, 9
	v_readlane_b32 s1, v241, 34
	v_mul_i32_i24_e32 v0, 64, v0
	s_mul_hi_i32 s28, s0, s31
	s_mul_i32 s29, s0, s31
	v_readlane_b32 s0, v241, 35
	s_ashr_i32 s5, s4, 6
	v_lshrrev_b32_e32 v5, 2, v3
	v_lshlrev_b32_e32 v6, 1, v3
	v_sub_u32_e32 v0, v1, v0
	v_readlane_b32 s1, v241, 36
	s_mov_b32 s42, s0
	s_lshl_b32 s26, s35, 8
	s_ashr_i32 s40, s4, 8
	s_lshl_b32 s50, s5, 10
	v_and_b32_e32 v5, 4, v5
	v_and_b32_e32 v6, 24, v6
	v_lshlrev_b32_e32 v2, 5, v2
	v_ashrrev_i16_sdwa v0, v207, sext(v0) dst_sel:DWORD dst_unused:UNUSED_PAD src0_sel:DWORD src1_sel:BYTE_0
	s_mul_i32 s1, s42, s31
	v_or3_b32 v4, v4, v5, v6
	v_and_b32_e32 v15, 32, v2
	v_bfe_i32 v16, v0, 0, 16
	s_mul_hi_i32 s0, s0, s31
	s_add_u32 s48, s8, s1
	v_mul_lo_u32 v4, v4, s35
	v_add_u32_e32 v0, v15, v16
	s_addc_u32 s49, s9, s0
	s_add_i32 s51, s50, 0
	v_add_lshl_u32 v172, v4, v0, 1
	s_add_i32 m0, s51, 0x10000
	v_mov_b32_e32 v183, v173
	global_load_lds_dwordx4 v172, s[48:49]
	s_add_i32 m0, s51, 0x12000
	s_add_u32 s0, s48, s26
	global_load_lds_dwordx4 v182, s[48:49]
	s_addc_u32 s1, s49, 0
	s_add_i32 m0, s51, 0x14000
	v_lshl_add_u64 v[4:5], s[0:1], 0, v[172:173]
	global_load_lds_dwordx4 v172, s[0:1]
	s_add_i32 m0, s51, 0x16000
	v_lshl_add_u64 v[6:7], s[0:1], 0, v[182:183]
	global_load_lds_dwordx4 v182, s[0:1]
	v_readlane_b32 s0, v242, 63
	v_readlane_b32 s1, v241, 0
	s_add_u32 s46, s0, s29
	v_mul_lo_u32 v17, v3, s35
	s_addc_u32 s47, s1, s28
	s_add_i32 s52, s51, 0x2000
	v_add_lshl_u32 v186, v0, v17, 1
	s_mov_b32 m0, s51
	s_add_u32 s0, s46, s26
	global_load_lds_dwordx4 v186, s[46:47]
	s_mov_b32 m0, s52
	s_addc_u32 s1, s47, 0
	s_add_i32 s53, s51, 0x4000
	global_load_lds_dwordx4 v184, s[46:47]
	s_mov_b32 m0, s53
	s_add_i32 s54, s51, 0x6000
	global_load_lds_dwordx4 v186, s[0:1]
	s_mov_b32 m0, s54
	v_mov_b32_e32 v187, v173
	global_load_lds_dwordx4 v184, s[0:1]
	v_mov_b32_e32 v185, v173
	s_cmp_eq_u32 s40, 1
	v_lshl_add_u64 v[0:1], s[48:49], 0, v[172:173]
	v_lshl_add_u64 v[2:3], s[48:49], 0, v[182:183]
	v_lshl_add_u64 v[8:9], s[46:47], 0, v[186:187]
	v_lshl_add_u64 v[10:11], s[46:47], 0, v[184:185]
	s_cselect_b64 s[0:1], -1, 0
	s_cmp_lg_u32 s40, 1
	s_cbranch_scc1 .LBB0_1402
	s_barrier

	.amdhsa_kernel _Z8mega_fwd1P
		.amdhsa_group_segment_fixed_size 0
		.amdhsa_private_segment_fixed_size 0
		.amdhsa_kernarg_size 536
		.amdhsa_user_sgpr_count 2
		.amdhsa_user_sgpr_dispatch_ptr 0
		.amdhsa_user_sgpr_queue_ptr 0
		.amdhsa_user_sgpr_kernarg_segment_ptr 1
		.amdhsa_user_sgpr_dispatch_id 0
		.amdhsa_user_sgpr_kernarg_preload_length 0
		.amdhsa_user_sgpr_kernarg_preload_offset 0
		.amdhsa_user_sgpr_private_segment_size 0
		.amdhsa_uses_dynamic_stack 0
		.amdhsa_enable_private_segment 0
		.amdhsa_system_sgpr_workgroup_id_x 1
		.amdhsa_system_sgpr_workgroup_id_y 0
		.amdhsa_system_sgpr_workgroup_id_z 0
		.amdhsa_system_sgpr_workgroup_info 0
		.amdhsa_system_vgpr_workitem_id 2
		.amdhsa_next_free_vgpr 243
		.amdhsa_next_free_sgpr 102
		.amdhsa_accum_offset 244
		.amdhsa_reserve_vcc 1
		.amdhsa_float_round_mode_32 0
		.amdhsa_float_round_mode_16_64 0
		.amdhsa_float_denorm_mode_32 3
		.amdhsa_float_denorm_mode_16_64 3
		.amdhsa_dx10_clamp 1
		.amdhsa_ieee_mode 1
		.amdhsa_fp16_overflow 0
		.amdhsa_tg_split 0
		.amdhsa_exception_fp_ieee_invalid_op 0
		.amdhsa_exception_fp_denorm_src 0
		.amdhsa_exception_fp_ieee_div_zero 0
		.amdhsa_exception_fp_ieee_overflow 0
		.amdhsa_exception_fp_ieee_underflow 0
		.amdhsa_exception_fp_ieee_inexact 0
		.amdhsa_exception_int_div_zero 0
	.end_amdhsa_kernel

amdhsa.kernels:
  - .agpr_count:     0
    .args:
      - .offset:         0
        .size:           280
        .value_kind:     by_value
      - .offset:         280
        .size:           4
        .value_kind:     hidden_block_count_x
      - .offset:         284
        .size:           4
        .value_kind:     hidden_block_count_y
      - .offset:         288
        .size:           4
        .value_kind:     hidden_block_count_z
      - .offset:         292
        .size:           2
        .value_kind:     hidden_group_size_x
      - .offset:         294
        .size:           2
        .value_kind:     hidden_group_size_y
      - .offset:         296
        .size:           2
        .value_kind:     hidden_group_size_z
      - .offset:         298
        .size:           2
        .value_kind:     hidden_remainder_x
      - .offset:         300
        .size:           2
        .value_kind:     hidden_remainder_y
      - .offset:         302
        .size:           2
        .value_kind:     hidden_remainder_z
      - .offset:         320
        .size:           8
        .value_kind:     hidden_global_offset_x
      - .offset:         328
        .size:           8
        .value_kind:     hidden_global_offset_y
      - .offset:         336
        .size:           8
        .value_kind:     hidden_global_offset_z
      - .offset:         344
        .size:           2
        .value_kind:     hidden_grid_dims
      - .offset:         368
        .size:           8
        .value_kind:     hidden_multigrid_sync_arg
      - .offset:         400
        .size:           4
        .value_kind:     hidden_dynamic_lds_size
    .group_segment_fixed_size: 0
    .kernarg_segment_align: 8
    .kernarg_segment_size: 536
    .language:       OpenCL C
    .language_version:
      - 2
      - 0
    .max_flat_workgroup_size: 512
    .name:           _Z8mega_fwd1P
    .private_segment_fixed_size: 0
    .sgpr_count:     108
    .sgpr_spill_count: 212
    .symbol:         _Z8mega_fwd1P.kd
    .uniform_work_group_size: 1
    .uses_dynamic_stack: false
    .vgpr_count:     243
    .vgpr_spill_count: 0
    .wavefront_size: 64
